# lnmod phases: non-temporal (nt) stores for the streamed f32 residual row writes
# speedup vs baseline: 1.0067x; 1.0067x over previous
.LBB0_147:
	s_or_b64 exec, exec, s[14:15]
	s_and_b64 s[0:1], exec, vcc
	s_or_b64 s[12:13], s[0:1], s[12:13]
	v_add_u32_e32 v50, 0x1000, v49
	v_lshrrev_b32_e32 v49, 12, v49
	s_movk_i32 s0, 0xfff
	v_add_u32_e32 v49, 1, v49
	v_cmp_lt_i32_e32 vcc, s0, v50
	s_movk_i32 s0, 0x6000
	v_lshl_add_u64 v[36:37], v[36:37], 0, s[6:7]
	v_cndmask_b32_e32 v49, 0, v49, vcc
	v_mad_u64_u32 v[50:51], s[0:1], v49, s0, v[40:41]
	s_mov_b64 s[0:1], 0x1000
	s_nop 0
	v_lshl_add_u64 v[52:53], v[50:51], 0, s[0:1]
	v_lshl_add_u64 v[58:59], v[50:51], 0, v[32:33]
	v_lshl_add_u64 v[54:55], v[52:53], 0, v[32:33]
	v_lshl_add_u64 v[60:61], v[52:53], 0, v[42:43]
	v_lshl_add_u64 v[62:63], v[52:53], 0, v[44:45]
	v_lshl_add_u64 v[64:65], v[52:53], 0, v[46:47]
	global_load_dwordx4 v[50:53], v[58:59], off
	s_nop 0
	global_load_dwordx4 v[54:57], v[54:55], off
	s_waitcnt vmcnt(0)
	v_pk_add_f32 v[56:57], v[56:57], 1.0 op_sel_hi:[1,0]
	v_pk_add_f32 v[54:55], v[54:55], 1.0 op_sel_hi:[1,0]
	v_pk_fma_f32 v[52:53], v[18:19], v[56:57], v[52:53]
	v_pk_fma_f32 v[50:51], v[16:17], v[54:55], v[50:51]
	v_cvt_pk_bf16_f32 v67, v52, v53
	v_cvt_pk_bf16_f32 v66, v50, v51
	global_load_dwordx4 v[50:53], v[58:59], off offset:1024
	global_load_dwordx4 v[54:57], v[60:61], off
	s_waitcnt vmcnt(0)
	v_pk_add_f32 v[56:57], v[56:57], 1.0 op_sel_hi:[1,0]
	v_pk_add_f32 v[54:55], v[54:55], 1.0 op_sel_hi:[1,0]
	v_pk_fma_f32 v[52:53], v[30:31], v[56:57], v[52:53]
	v_pk_fma_f32 v[50:51], v[28:29], v[54:55], v[50:51]
	v_cvt_pk_bf16_f32 v61, v52, v53
	v_cvt_pk_bf16_f32 v60, v50, v51
	global_load_dwordx4 v[50:53], v[58:59], off offset:2048
	global_load_dwordx4 v[54:57], v[62:63], off
	s_waitcnt vmcnt(0)
	v_pk_add_f32 v[56:57], v[56:57], 1.0 op_sel_hi:[1,0]
	v_pk_add_f32 v[54:55], v[54:55], 1.0 op_sel_hi:[1,0]
	v_pk_fma_f32 v[52:53], v[26:27], v[56:57], v[52:53]
	v_pk_fma_f32 v[50:51], v[24:25], v[54:55], v[50:51]
	v_cvt_pk_bf16_f32 v63, v52, v53
	v_cvt_pk_bf16_f32 v62, v50, v51
	global_load_dwordx4 v[50:53], v[58:59], off offset:3072
	global_load_dwordx4 v[54:57], v[64:65], off
	s_nop 0
	global_store_dwordx4 v[38:39], v[16:19], off nt
	global_store_dwordx4 v[38:39], v[28:31], off offset:1024 nt
	global_store_dwordx4 v[38:39], v[24:27], off offset:2048 nt
	global_store_dwordx4 v[38:39], v[20:23], off offset:3072 nt
	global_store_dwordx2 v[34:35], v[66:67], off offset:-1024
	global_store_dwordx2 v[34:35], v[60:61], off offset:-512
	global_store_dwordx2 v[34:35], v[62:63], off
	v_lshl_add_u64 v[38:39], v[38:39], 0, s[10:11]
	v_mov_b32_e32 v49, v48
	v_mov_b64_e32 v[28:29], v[4:5]
	v_mov_b64_e32 v[30:31], v[6:7]
	v_mov_b64_e32 v[24:25], v[8:9]
	v_mov_b64_e32 v[26:27], v[10:11]
	s_waitcnt vmcnt(7)
	v_pk_add_f32 v[16:17], v[56:57], 1.0 op_sel_hi:[1,0]
	v_pk_add_f32 v[18:19], v[54:55], 1.0 op_sel_hi:[1,0]
	v_pk_fma_f32 v[16:17], v[22:23], v[16:17], v[52:53]
	v_pk_fma_f32 v[18:19], v[20:21], v[18:19], v[50:51]
	v_cvt_pk_bf16_f32 v17, v16, v17
	v_cvt_pk_bf16_f32 v16, v18, v19
	global_store_dwordx2 v[34:35], v[16:17], off offset:512
	v_lshl_add_u64 v[34:35], v[34:35], 0, s[8:9]
	v_mov_b64_e32 v[16:17], v[0:1]
	v_mov_b64_e32 v[18:19], v[2:3]
	v_mov_b64_e32 v[20:21], v[12:13]
	v_mov_b64_e32 v[22:23], v[14:15]
	s_andn2_b64 exec, exec, s[12:13]
	s_cbranch_execz .LBB0_150

.LBB0_1462:
	s_or_b64 exec, exec, s[14:15]
	s_and_b64 s[0:1], exec, vcc
	v_add_u32_e32 v65, 0xfffff000, v64
	s_or_b64 s[12:13], s[0:1], s[12:13]
	v_lshrrev_b32_e32 v65, 12, v65
	s_movk_i32 s0, 0xfff
	v_add_u32_e32 v65, 1, v65
	v_cmp_lt_i32_e32 vcc, s0, v64
	s_movk_i32 s0, 0x6000
	v_mov_b32_e32 v104, v56
	v_cndmask_b32_e32 v64, 0, v65, vcc
	v_mad_u64_u32 v[64:65], s[0:1], v64, s0, v[76:77]
	s_mov_b64 s[0:1], 0x3000
	s_nop 0
	v_lshl_add_u64 v[86:87], v[64:65], 0, s[0:1]
	s_mov_b64 s[0:1], 0x4000
	v_lshl_add_u64 v[88:89], v[64:65], 0, s[0:1]
	v_lshl_add_u64 v[102:103], v[86:87], 0, v[78:79]
	v_lshl_add_u64 v[96:97], v[86:87], 0, v[80:81]
	v_lshl_add_u64 v[92:93], v[86:87], 0, v[82:83]
	v_lshl_add_u64 v[64:65], v[86:87], 0, v[84:85]
	v_mov_b32_e32 v86, v57
	v_mov_b32_e32 v87, v61
	v_mov_b32_e32 v105, v60
	v_pk_add_f32 v[86:87], v[86:87], v[104:105]
	v_mov_b32_e32 v104, v58
	v_mov_b32_e32 v105, v62
	v_pk_add_f32 v[86:87], v[104:105], v[86:87]
	v_mov_b32_e32 v104, v59
	v_mov_b32_e32 v105, v63
	v_pk_add_f32 v[86:87], v[104:105], v[86:87]
	v_mov_b32_e32 v104, v48
	v_add_f32_e32 v87, 0, v87
	v_add_f32_e32 v106, v86, v87
	v_mov_b32_e32 v86, v49
	v_mov_b32_e32 v87, v53
	v_mov_b32_e32 v105, v52
	v_pk_add_f32 v[86:87], v[86:87], v[104:105]
	v_mov_b32_e32 v104, v50
	v_mov_b32_e32 v105, v54
	v_pk_add_f32 v[86:87], v[104:105], v[86:87]
	v_mov_b32_e32 v104, v51
	v_mov_b32_e32 v105, v55
	v_pk_add_f32 v[86:87], v[104:105], v[86:87]
	s_mov_b32 s0, 0x800000
	v_add_f32_e32 v87, v87, v106
	v_add_f32_e32 v86, v86, v87
	v_lshl_add_u64 v[90:91], v[88:89], 0, v[78:79]
	v_lshl_add_u64 v[94:95], v[88:89], 0, v[80:81]
	v_add_f32_dpp v86, v86, v86 row_ror:8 row_mask:0xf bank_mask:0xf bound_ctrl:1
	v_lshl_add_u64 v[66:67], v[88:89], 0, v[82:83]
	v_lshl_add_u64 v[88:89], v[88:89], 0, v[84:85]
	v_add_f32_dpp v86, v86, v86 row_ror:4 row_mask:0xf bank_mask:0xf bound_ctrl:1
	v_lshl_add_u64 v[74:75], v[74:75], 0, s[10:11]
	s_nop 0
	v_add_f32_dpp v86, v86, v86 row_ror:2 row_mask:0xf bank_mask:0xf bound_ctrl:1
	s_nop 1
	v_add_f32_dpp v86, v86, v86 row_ror:1 row_mask:0xf bank_mask:0xf bound_ctrl:1
	ds_bpermute_b32 v87, v98, v86
	s_waitcnt lgkmcnt(0)
	v_add_f32_e32 v86, v86, v87
	ds_bpermute_b32 v87, v99, v86
	s_waitcnt lgkmcnt(0)
	v_add_f32_e32 v86, v86, v87
	v_mul_f32_e32 v104, 0x3a800000, v86
	v_pk_add_f32 v[60:61], v[60:61], v[104:105] op_sel_hi:[1,0] neg_lo:[0,1] neg_hi:[0,1]
	v_pk_add_f32 v[56:57], v[56:57], v[104:105] op_sel_hi:[1,0] neg_lo:[0,1] neg_hi:[0,1]
	v_mov_b32_e32 v108, v61
	v_mov_b32_e32 v109, v57
	v_pk_add_f32 v[62:63], v[62:63], v[104:105] op_sel_hi:[1,0] neg_lo:[0,1] neg_hi:[0,1]
	v_pk_add_f32 v[58:59], v[58:59], v[104:105] op_sel_hi:[1,0] neg_lo:[0,1] neg_hi:[0,1]
	v_mov_b32_e32 v106, v60
	v_mov_b32_e32 v107, v56
	v_pk_mul_f32 v[108:109], v[108:109], v[108:109]
	v_pk_add_f32 v[52:53], v[52:53], v[104:105] op_sel_hi:[1,0] neg_lo:[0,1] neg_hi:[0,1]
	v_pk_fma_f32 v[106:107], v[106:107], v[106:107], v[108:109]
	v_mov_b32_e32 v108, v62
	v_mov_b32_e32 v109, v58
	v_pk_add_f32 v[48:49], v[48:49], v[104:105] op_sel_hi:[1,0] neg_lo:[0,1] neg_hi:[0,1]
	v_pk_fma_f32 v[106:107], v[108:109], v[108:109], v[106:107]
	v_mov_b32_e32 v108, v49
	v_mov_b32_e32 v109, v53
	v_pk_add_f32 v[54:55], v[54:55], v[104:105] op_sel_hi:[1,0] neg_lo:[0,1] neg_hi:[0,1]
	v_pk_add_f32 v[50:51], v[50:51], v[104:105] op_sel_hi:[1,0] neg_lo:[0,1] neg_hi:[0,1]
	v_mov_b32_e32 v104, v48
	v_mov_b32_e32 v105, v52
	v_pk_mul_f32 v[108:109], v[108:109], v[108:109]
	v_mov_b32_e32 v110, v63
	v_mov_b32_e32 v111, v59
	v_pk_fma_f32 v[104:105], v[104:105], v[104:105], v[108:109]
	v_mov_b32_e32 v108, v50
	v_mov_b32_e32 v109, v54
	v_pk_fma_f32 v[106:107], v[110:111], v[110:111], v[106:107]
	v_mov_b32_e32 v110, v51
	v_mov_b32_e32 v111, v55
	v_pk_fma_f32 v[104:105], v[108:109], v[108:109], v[104:105]
	v_add_f32_e32 v106, v106, v107
	v_pk_fma_f32 v[104:105], v[110:111], v[110:111], v[104:105]
	v_lshl_add_u64 v[86:87], v[70:71], 0, v[68:69]
	v_add_f32_e32 v105, v105, v106
	v_add_f32_e32 v104, v104, v105
	v_lshl_add_u64 v[70:71], v[70:71], 0, s[10:11]
	s_nop 0
	v_add_f32_dpp v104, v104, v104 row_ror:8 row_mask:0xf bank_mask:0xf bound_ctrl:1
	s_nop 1
	v_add_f32_dpp v104, v104, v104 row_ror:4 row_mask:0xf bank_mask:0xf bound_ctrl:1
	s_nop 1
	v_add_f32_dpp v104, v104, v104 row_ror:2 row_mask:0xf bank_mask:0xf bound_ctrl:1
	s_nop 1
	v_add_f32_dpp v104, v104, v104 row_ror:1 row_mask:0xf bank_mask:0xf bound_ctrl:1
	ds_bpermute_b32 v105, v98, v104
	s_waitcnt lgkmcnt(0)
	v_add_f32_e32 v104, v104, v105
	ds_bpermute_b32 v105, v99, v104
	s_waitcnt lgkmcnt(0)
	v_add_f32_e32 v104, v104, v105
	v_fmamk_f32 v104, v104, 0x3a800000, v100
	v_cmp_gt_f32_e32 vcc, s0, v104
	v_mul_f32_e32 v105, 0x4b800000, v104
	s_nop 0
	v_cndmask_b32_e32 v104, v104, v105, vcc
	v_rsq_f32_e32 v104, v104
	s_nop 0
	v_mul_f32_e32 v105, 0x45800000, v104
	v_cndmask_b32_e32 v104, v104, v105, vcc
	v_pk_mul_f32 v[60:61], v[60:61], v[104:105] op_sel_hi:[1,0]
	v_pk_mul_f32 v[62:63], v[62:63], v[104:105] op_sel_hi:[1,0]
	v_pk_mul_f32 v[56:57], v[56:57], v[104:105] op_sel_hi:[1,0]
	v_pk_mul_f32 v[58:59], v[58:59], v[104:105] op_sel_hi:[1,0]
	v_pk_mul_f32 v[52:53], v[52:53], v[104:105] op_sel_hi:[1,0]
	v_pk_mul_f32 v[54:55], v[54:55], v[104:105] op_sel_hi:[1,0]
	v_pk_mul_f32 v[48:49], v[48:49], v[104:105] op_sel_hi:[1,0]
	v_pk_mul_f32 v[50:51], v[50:51], v[104:105] op_sel_hi:[1,0]
	global_load_dwordx4 v[102:105], v[102:103], off
	s_nop 0
	global_load_dwordx4 v[106:109], v[90:91], off
	v_pk_fma_f32 v[60:61], v[0:1], v[60:61], v[4:5]
	v_pk_fma_f32 v[62:63], v[2:3], v[62:63], v[6:7]
	v_pk_fma_f32 v[56:57], v[8:9], v[56:57], v[12:13]
	v_pk_fma_f32 v[58:59], v[10:11], v[58:59], v[14:15]
	v_pk_fma_f32 v[52:53], v[16:17], v[52:53], v[20:21]
	v_pk_fma_f32 v[54:55], v[18:19], v[54:55], v[22:23]
	v_pk_fma_f32 v[48:49], v[24:25], v[48:49], v[28:29]
	v_pk_fma_f32 v[50:51], v[26:27], v[50:51], v[30:31]
	s_waitcnt vmcnt(0)
	v_pk_add_f32 v[90:91], v[108:109], 1.0 op_sel_hi:[1,0]
	v_pk_add_f32 v[106:107], v[106:107], 1.0 op_sel_hi:[1,0]
	v_pk_fma_f32 v[90:91], v[90:91], v[62:63], v[104:105]
	v_pk_fma_f32 v[102:103], v[106:107], v[60:61], v[102:103]
	v_cvt_pk_bf16_f32 v91, v90, v91
	v_cvt_pk_bf16_f32 v90, v102, v103
	global_load_dwordx4 v[102:105], v[96:97], off
	s_nop 0
	global_load_dwordx4 v[94:97], v[94:95], off
	s_waitcnt vmcnt(0)
	v_pk_add_f32 v[94:95], v[94:95], 1.0 op_sel_hi:[1,0]
	v_pk_add_f32 v[96:97], v[96:97], 1.0 op_sel_hi:[1,0]
	v_pk_fma_f32 v[94:95], v[94:95], v[56:57], v[102:103]
	v_pk_fma_f32 v[96:97], v[96:97], v[58:59], v[104:105]
	v_cvt_pk_bf16_f32 v94, v94, v94
	v_cvt_pk_bf16_f32 v104, v95, v95
	v_cvt_pk_bf16_f32 v95, v96, v96
	v_cvt_pk_bf16_f32 v96, v97, v97
	v_perm_b32 v94, v104, v94, s7
	global_load_dwordx4 v[102:105], v[92:93], off
	global_load_dwordx4 v[106:109], v[66:67], off
	v_perm_b32 v95, v96, v95, s7
	s_waitcnt vmcnt(0)
	v_pk_add_f32 v[66:67], v[108:109], 1.0 op_sel_hi:[1,0]
	v_pk_add_f32 v[92:93], v[106:107], 1.0 op_sel_hi:[1,0]
	v_pk_fma_f32 v[66:67], v[66:67], v[54:55], v[104:105]
	v_pk_fma_f32 v[92:93], v[92:93], v[52:53], v[102:103]
	v_cvt_pk_bf16_f32 v92, v92, v92
	v_cvt_pk_bf16_f32 v102, v93, v93
	v_cvt_pk_bf16_f32 v93, v66, v67
	v_perm_b32 v92, v102, v92, s7
	global_load_dwordx4 v[64:67], v[64:65], off
	s_nop 0
	global_load_dwordx4 v[102:105], v[88:89], off
	s_nop 0
	global_store_dwordx4 v[86:87], v[60:63], off nt
	global_store_dwordx4 v[86:87], v[56:59], off offset:1024 nt
	global_store_dwordx4 v[86:87], v[52:55], off offset:2048 nt
	global_store_dwordx4 v[86:87], v[48:51], off offset:3072 nt
	global_store_dwordx2 v[72:73], v[90:91], off
	global_store_dwordx2 v[72:73], v[94:95], off offset:512
	global_store_dwordx2 v[72:73], v[92:93], off offset:1024
	v_mov_b64_e32 v[60:61], v[32:33]
	v_mov_b64_e32 v[62:63], v[34:35]
	v_mov_b64_e32 v[56:57], v[36:37]
	v_mov_b64_e32 v[58:59], v[38:39]
	s_waitcnt vmcnt(7)
	v_pk_add_f32 v[52:53], v[104:105], 1.0 op_sel_hi:[1,0]
	v_pk_add_f32 v[54:55], v[102:103], 1.0 op_sel_hi:[1,0]
	v_pk_fma_f32 v[50:51], v[52:53], v[50:51], v[66:67]
	v_pk_fma_f32 v[48:49], v[54:55], v[48:49], v[64:65]
	v_cvt_pk_bf16_f32 v48, v48, v48
	v_cvt_pk_bf16_f32 v54, v49, v49
	v_cvt_pk_bf16_f32 v49, v50, v50
	v_cvt_pk_bf16_f32 v50, v51, v51
	v_perm_b32 v49, v50, v49, s7
	v_perm_b32 v48, v54, v48, s7
	global_store_dwordx2 v[72:73], v[48:49], off offset:1536
	v_lshl_add_u64 v[72:73], v[72:73], 0, s[8:9]
	v_mov_b32_e32 v64, v101
	v_mov_b64_e32 v[52:53], v[40:41]
	v_mov_b64_e32 v[54:55], v[42:43]
	v_mov_b64_e32 v[48:49], v[44:45]
	v_mov_b64_e32 v[50:51], v[46:47]
	s_andn2_b64 exec, exec, s[12:13]
	s_cbranch_execz .LBB0_1465

.LBB0_1633:
	s_or_b64 exec, exec, s[14:15]
	s_and_b64 s[0:1], exec, vcc
	v_add_u32_e32 v65, 0xfffff000, v64
	s_or_b64 s[12:13], s[0:1], s[12:13]
	v_lshrrev_b32_e32 v65, 12, v65
	s_movk_i32 s0, 0xfff
	v_add_u32_e32 v65, 6, v65
	v_cmp_lt_i32_e32 vcc, s0, v64
	s_movk_i32 s0, 0x6000
	v_mov_b32_e32 v94, v56
	v_cndmask_b32_e32 v64, 5, v65, vcc
	v_mad_u64_u32 v[64:65], s[0:1], v64, s0, v[76:77]
	s_mov_b64 s[0:1], 0x1000
	s_nop 0
	v_lshl_add_u64 v[86:87], v[64:65], 0, s[0:1]
	v_lshl_add_u64 v[90:91], v[86:87], 0, v[78:79]
	v_lshl_add_u64 v[92:93], v[86:87], 0, v[80:81]
	v_lshl_add_u64 v[66:67], v[86:87], 0, v[82:83]
	v_lshl_add_u64 v[88:89], v[86:87], 0, v[84:85]
	v_mov_b32_e32 v86, v57
	v_mov_b32_e32 v87, v61
	v_mov_b32_e32 v95, v60
	v_pk_add_f32 v[86:87], v[86:87], v[94:95]
	v_mov_b32_e32 v94, v58
	v_mov_b32_e32 v95, v62
	v_pk_add_f32 v[86:87], v[94:95], v[86:87]
	v_mov_b32_e32 v94, v59
	v_mov_b32_e32 v95, v63
	v_pk_add_f32 v[86:87], v[94:95], v[86:87]
	v_mov_b32_e32 v94, v48
	v_add_f32_e32 v87, 0, v87
	v_add_f32_e32 v100, v86, v87
	v_mov_b32_e32 v86, v49
	v_mov_b32_e32 v87, v53
	v_mov_b32_e32 v95, v52
	v_pk_add_f32 v[86:87], v[86:87], v[94:95]
	v_mov_b32_e32 v94, v50
	v_mov_b32_e32 v95, v54
	v_pk_add_f32 v[86:87], v[94:95], v[86:87]
	v_mov_b32_e32 v94, v51
	v_mov_b32_e32 v95, v55
	v_pk_add_f32 v[86:87], v[94:95], v[86:87]
	v_lshl_add_u64 v[64:65], v[64:65], 0, v[78:79]
	v_add_f32_e32 v87, v87, v100
	v_add_f32_e32 v86, v86, v87
	s_mov_b32 s0, 0x800000
	v_lshl_add_u64 v[74:75], v[74:75], 0, s[10:11]
	v_add_f32_dpp v86, v86, v86 row_ror:8 row_mask:0xf bank_mask:0xf bound_ctrl:1
	s_nop 1
	v_add_f32_dpp v86, v86, v86 row_ror:4 row_mask:0xf bank_mask:0xf bound_ctrl:1
	s_nop 1
	v_add_f32_dpp v86, v86, v86 row_ror:2 row_mask:0xf bank_mask:0xf bound_ctrl:1
	s_nop 1
	v_add_f32_dpp v86, v86, v86 row_ror:1 row_mask:0xf bank_mask:0xf bound_ctrl:1
	ds_bpermute_b32 v87, v96, v86
	s_waitcnt lgkmcnt(0)
	v_add_f32_e32 v86, v86, v87
	ds_bpermute_b32 v87, v97, v86
	s_waitcnt lgkmcnt(0)
	v_add_f32_e32 v86, v86, v87
	v_mul_f32_e32 v94, 0x3a800000, v86
	v_pk_add_f32 v[60:61], v[60:61], v[94:95] op_sel_hi:[1,0] neg_lo:[0,1] neg_hi:[0,1]
	v_pk_add_f32 v[56:57], v[56:57], v[94:95] op_sel_hi:[1,0] neg_lo:[0,1] neg_hi:[0,1]
	v_mov_b32_e32 v102, v61
	v_mov_b32_e32 v103, v57
	v_pk_add_f32 v[62:63], v[62:63], v[94:95] op_sel_hi:[1,0] neg_lo:[0,1] neg_hi:[0,1]
	v_pk_add_f32 v[58:59], v[58:59], v[94:95] op_sel_hi:[1,0] neg_lo:[0,1] neg_hi:[0,1]
	v_mov_b32_e32 v100, v60
	v_mov_b32_e32 v101, v56
	v_pk_mul_f32 v[102:103], v[102:103], v[102:103]
	v_pk_add_f32 v[52:53], v[52:53], v[94:95] op_sel_hi:[1,0] neg_lo:[0,1] neg_hi:[0,1]
	v_pk_fma_f32 v[100:101], v[100:101], v[100:101], v[102:103]
	v_mov_b32_e32 v102, v62
	v_mov_b32_e32 v103, v58
	v_pk_add_f32 v[48:49], v[48:49], v[94:95] op_sel_hi:[1,0] neg_lo:[0,1] neg_hi:[0,1]
	v_pk_fma_f32 v[100:101], v[102:103], v[102:103], v[100:101]
	v_mov_b32_e32 v102, v49
	v_mov_b32_e32 v103, v53
	v_pk_add_f32 v[54:55], v[54:55], v[94:95] op_sel_hi:[1,0] neg_lo:[0,1] neg_hi:[0,1]
	v_pk_add_f32 v[50:51], v[50:51], v[94:95] op_sel_hi:[1,0] neg_lo:[0,1] neg_hi:[0,1]
	v_mov_b32_e32 v94, v48
	v_mov_b32_e32 v95, v52
	v_pk_mul_f32 v[102:103], v[102:103], v[102:103]
	v_mov_b32_e32 v104, v63
	v_mov_b32_e32 v105, v59
	v_pk_fma_f32 v[94:95], v[94:95], v[94:95], v[102:103]
	v_mov_b32_e32 v102, v50
	v_mov_b32_e32 v103, v54
	v_pk_fma_f32 v[100:101], v[104:105], v[104:105], v[100:101]
	v_mov_b32_e32 v104, v51
	v_mov_b32_e32 v105, v55
	v_pk_fma_f32 v[94:95], v[102:103], v[102:103], v[94:95]
	v_add_f32_e32 v100, v100, v101
	v_pk_fma_f32 v[94:95], v[104:105], v[104:105], v[94:95]
	v_lshl_add_u64 v[86:87], v[70:71], 0, v[68:69]
	v_add_f32_e32 v95, v95, v100
	global_load_dwordx4 v[100:103], v[64:65], off
	global_load_dwordx4 v[104:107], v[90:91], off
	v_add_f32_e32 v94, v94, v95
	v_lshl_add_u64 v[70:71], v[70:71], 0, s[10:11]
	s_waitcnt vmcnt(0)
	v_pk_add_f32 v[90:91], v[106:107], 1.0 op_sel_hi:[1,0]
	v_add_f32_dpp v94, v94, v94 row_ror:8 row_mask:0xf bank_mask:0xf bound_ctrl:1
	s_nop 1
	v_add_f32_dpp v94, v94, v94 row_ror:4 row_mask:0xf bank_mask:0xf bound_ctrl:1
	s_nop 1
	v_add_f32_dpp v94, v94, v94 row_ror:2 row_mask:0xf bank_mask:0xf bound_ctrl:1
	s_nop 1
	v_add_f32_dpp v94, v94, v94 row_ror:1 row_mask:0xf bank_mask:0xf bound_ctrl:1
	ds_bpermute_b32 v95, v96, v94
	s_waitcnt lgkmcnt(0)
	v_add_f32_e32 v94, v94, v95
	ds_bpermute_b32 v95, v97, v94
	s_waitcnt lgkmcnt(0)
	v_add_f32_e32 v94, v94, v95
	v_fmamk_f32 v94, v94, 0x3a800000, v98
	v_cmp_gt_f32_e32 vcc, s0, v94
	v_mul_f32_e32 v95, 0x4b800000, v94
	s_nop 0
	v_cndmask_b32_e32 v94, v94, v95, vcc
	v_rsq_f32_e32 v94, v94
	s_nop 0
	v_mul_f32_e32 v95, 0x45800000, v94
	v_cndmask_b32_e32 v94, v94, v95, vcc
	v_pk_mul_f32 v[60:61], v[60:61], v[94:95] op_sel_hi:[1,0]
	v_pk_mul_f32 v[62:63], v[62:63], v[94:95] op_sel_hi:[1,0]
	v_pk_fma_f32 v[60:61], v[0:1], v[60:61], v[4:5]
	v_pk_fma_f32 v[62:63], v[2:3], v[62:63], v[6:7]
	v_pk_mul_f32 v[56:57], v[56:57], v[94:95] op_sel_hi:[1,0]
	v_pk_mul_f32 v[58:59], v[58:59], v[94:95] op_sel_hi:[1,0]
	v_pk_mul_f32 v[52:53], v[52:53], v[94:95] op_sel_hi:[1,0]
	v_pk_mul_f32 v[54:55], v[54:55], v[94:95] op_sel_hi:[1,0]
	v_pk_mul_f32 v[48:49], v[48:49], v[94:95] op_sel_hi:[1,0]
	v_pk_mul_f32 v[50:51], v[50:51], v[94:95] op_sel_hi:[1,0]
	v_pk_add_f32 v[94:95], v[104:105], 1.0 op_sel_hi:[1,0]
	v_pk_fma_f32 v[90:91], v[90:91], v[62:63], v[102:103]
	v_pk_fma_f32 v[94:95], v[94:95], v[60:61], v[100:101]
	v_cvt_pk_bf16_f32 v91, v90, v91
	v_cvt_pk_bf16_f32 v90, v94, v95
	global_load_dwordx4 v[100:103], v[64:65], off offset:1024
	s_nop 0
	global_load_dwordx4 v[92:95], v[92:93], off
	v_pk_fma_f32 v[56:57], v[8:9], v[56:57], v[12:13]
	v_pk_fma_f32 v[58:59], v[10:11], v[58:59], v[14:15]
	v_pk_fma_f32 v[52:53], v[16:17], v[52:53], v[20:21]
	v_pk_fma_f32 v[54:55], v[18:19], v[54:55], v[22:23]
	v_pk_fma_f32 v[48:49], v[24:25], v[48:49], v[28:29]
	v_pk_fma_f32 v[50:51], v[26:27], v[50:51], v[30:31]
	s_waitcnt vmcnt(0)
	v_pk_add_f32 v[92:93], v[92:93], 1.0 op_sel_hi:[1,0]
	v_pk_add_f32 v[94:95], v[94:95], 1.0 op_sel_hi:[1,0]
	v_pk_fma_f32 v[92:93], v[92:93], v[56:57], v[100:101]
	v_pk_fma_f32 v[94:95], v[94:95], v[58:59], v[102:103]
	v_cvt_pk_bf16_f32 v92, v92, v92
	v_cvt_pk_bf16_f32 v102, v93, v93
	v_cvt_pk_bf16_f32 v93, v94, v94
	v_cvt_pk_bf16_f32 v94, v95, v95
	v_perm_b32 v92, v102, v92, s7
	global_load_dwordx4 v[100:103], v[64:65], off offset:2048
	global_load_dwordx4 v[104:107], v[66:67], off
	v_perm_b32 v93, v94, v93, s7
	s_waitcnt vmcnt(0)
	v_pk_add_f32 v[66:67], v[106:107], 1.0 op_sel_hi:[1,0]
	v_pk_add_f32 v[94:95], v[104:105], 1.0 op_sel_hi:[1,0]
	v_pk_fma_f32 v[66:67], v[66:67], v[54:55], v[102:103]
	v_pk_fma_f32 v[94:95], v[94:95], v[52:53], v[100:101]
	v_cvt_pk_bf16_f32 v94, v94, v94
	v_cvt_pk_bf16_f32 v102, v95, v95
	v_cvt_pk_bf16_f32 v95, v66, v67
	v_perm_b32 v94, v102, v94, s7
	global_load_dwordx4 v[64:67], v[64:65], off offset:3072
	s_nop 0
	global_load_dwordx4 v[100:103], v[88:89], off
	s_nop 0
	global_store_dwordx4 v[86:87], v[60:63], off nt
	global_store_dwordx4 v[86:87], v[56:59], off offset:1024 nt
	global_store_dwordx4 v[86:87], v[52:55], off offset:2048 nt
	global_store_dwordx4 v[86:87], v[48:51], off offset:3072 nt
	global_store_dwordx2 v[72:73], v[90:91], off
	global_store_dwordx2 v[72:73], v[92:93], off offset:512
	global_store_dwordx2 v[72:73], v[94:95], off offset:1024
	v_mov_b64_e32 v[60:61], v[32:33]
	v_mov_b64_e32 v[62:63], v[34:35]
	v_mov_b64_e32 v[56:57], v[36:37]
	v_mov_b64_e32 v[58:59], v[38:39]
	s_waitcnt vmcnt(7)
	v_pk_add_f32 v[52:53], v[102:103], 1.0 op_sel_hi:[1,0]
	v_pk_add_f32 v[54:55], v[100:101], 1.0 op_sel_hi:[1,0]
	v_pk_fma_f32 v[50:51], v[52:53], v[50:51], v[66:67]
	v_pk_fma_f32 v[48:49], v[54:55], v[48:49], v[64:65]
	v_cvt_pk_bf16_f32 v48, v48, v48
	v_cvt_pk_bf16_f32 v54, v49, v49
	v_cvt_pk_bf16_f32 v49, v50, v50
	v_cvt_pk_bf16_f32 v50, v51, v51
	v_perm_b32 v49, v50, v49, s7
	v_perm_b32 v48, v54, v48, s7
	global_store_dwordx2 v[72:73], v[48:49], off offset:1536
	v_lshl_add_u64 v[72:73], v[72:73], 0, s[8:9]
	v_mov_b32_e32 v64, v99
	v_mov_b64_e32 v[52:53], v[40:41]
	v_mov_b64_e32 v[54:55], v[42:43]
	v_mov_b64_e32 v[48:49], v[44:45]
	v_mov_b64_e32 v[50:51], v[46:47]
	s_andn2_b64 exec, exec, s[12:13]
	s_cbranch_execz .LBB0_1636

.LBB0_2948:
	s_or_b64 exec, exec, s[18:19]
	v_add_u32_e32 v87, 0xfffff000, v82
	v_mov_b32_e32 v90, v57
	v_mov_b32_e32 v91, v61
	v_mov_b32_e32 v92, v56
	v_mov_b32_e32 v93, v60
	v_lshrrev_b32_e32 v87, 12, v87
	v_pk_add_f32 v[90:91], v[90:91], v[92:93]
	v_mov_b32_e32 v92, v58
	v_mov_b32_e32 v93, v62
	v_add_u32_e32 v87, 6, v87
	v_cmp_lt_i32_e64 s[0:1], s7, v82
	v_pk_add_f32 v[90:91], v[92:93], v[90:91]
	v_mov_b32_e32 v92, v59
	v_mov_b32_e32 v93, v63
	v_cndmask_b32_e64 v82, 5, v87, s[0:1]
	v_pk_add_f32 v[90:91], v[92:93], v[90:91]
	v_mad_u64_u32 v[88:89], s[0:1], v82, s20, v[72:73]
	v_add_f32_e32 v82, 0, v91
	v_add_f32_e32 v82, v90, v82
	v_mov_b32_e32 v90, v49
	v_mov_b32_e32 v91, v53
	v_mov_b32_e32 v92, v48
	v_mov_b32_e32 v93, v52
	v_pk_add_f32 v[90:91], v[90:91], v[92:93]
	v_mov_b32_e32 v92, v50
	v_mov_b32_e32 v93, v54
	v_pk_add_f32 v[90:91], v[92:93], v[90:91]
	v_mov_b32_e32 v92, v51
	v_mov_b32_e32 v93, v55
	v_pk_add_f32 v[90:91], v[92:93], v[90:91]
	v_lshl_add_u64 v[100:101], v[88:89], 0, s[14:15]
	v_add_f32_e32 v82, v91, v82
	v_add_f32_e32 v82, v90, v82
	v_lshl_add_u64 v[96:97], v[88:89], 0, s[16:17]
	v_lshl_add_u64 v[92:93], v[100:101], 0, v[74:75]
	v_add_f32_dpp v82, v82, v82 row_ror:8 row_mask:0xf bank_mask:0xf bound_ctrl:1
	v_lshl_add_u64 v[94:95], v[96:97], 0, v[74:75]
	v_lshl_add_u64 v[98:99], v[100:101], 0, v[76:77]
	v_add_f32_dpp v82, v82, v82 row_ror:4 row_mask:0xf bank_mask:0xf bound_ctrl:1
	v_lshl_add_u64 v[102:103], v[96:97], 0, v[76:77]
	v_lshl_add_u64 v[104:105], v[100:101], 0, v[78:79]
	v_add_f32_dpp v82, v82, v82 row_ror:2 row_mask:0xf bank_mask:0xf bound_ctrl:1
	v_lshl_add_u64 v[106:107], v[96:97], 0, v[78:79]
	v_lshl_add_u64 v[96:97], v[96:97], 0, v[80:81]
	v_add_f32_dpp v82, v82, v82 row_ror:1 row_mask:0xf bank_mask:0xf bound_ctrl:1
	ds_bpermute_b32 v87, v84, v82
	v_lshl_add_u64 v[100:101], v[100:101], 0, v[80:81]
	v_lshl_add_u64 v[124:125], v[66:67], 0, v[64:65]
	s_and_b64 s[18:19], exec, vcc
	s_or_b64 s[12:13], s[18:19], s[12:13]
	s_waitcnt lgkmcnt(0)
	v_add_f32_e32 v82, v82, v87
	ds_bpermute_b32 v87, v85, v82
	v_lshl_add_u64 v[70:71], v[70:71], 0, s[10:11]
	v_lshl_add_u64 v[66:67], v[66:67], 0, s[10:11]
	s_waitcnt lgkmcnt(0)
	v_add_f32_e32 v82, v82, v87
	v_mul_f32_e32 v82, 0x3a800000, v82
	v_pk_add_f32 v[108:109], v[60:61], v[82:83] op_sel_hi:[1,0] neg_lo:[0,1] neg_hi:[0,1]
	v_pk_add_f32 v[112:113], v[56:57], v[82:83] op_sel_hi:[1,0] neg_lo:[0,1] neg_hi:[0,1]
	v_pk_add_f32 v[114:115], v[58:59], v[82:83] op_sel_hi:[1,0] neg_lo:[0,1] neg_hi:[0,1]
	v_mov_b32_e32 v58, v109
	v_mov_b32_e32 v59, v113
	v_pk_add_f32 v[110:111], v[62:63], v[82:83] op_sel_hi:[1,0] neg_lo:[0,1] neg_hi:[0,1]
	v_mov_b32_e32 v56, v108
	v_mov_b32_e32 v57, v112
	v_pk_mul_f32 v[58:59], v[58:59], v[58:59]
	v_mov_b32_e32 v118, v110
	v_pk_fma_f32 v[116:117], v[56:57], v[56:57], v[58:59]
	v_mov_b32_e32 v119, v114
	global_load_dwordx4 v[60:63], v[92:93], off
	global_load_dwordx4 v[88:91], v[94:95], off
	v_mov_b32_e32 v120, v111
	v_mov_b32_e32 v121, v115
	global_load_dwordx4 v[56:59], v[98:99], off
	global_load_dwordx4 v[92:95], v[102:103], off
	v_pk_fma_f32 v[98:99], v[118:119], v[118:119], v[116:117]
	v_pk_add_f32 v[116:117], v[52:53], v[82:83] op_sel_hi:[1,0] neg_lo:[0,1] neg_hi:[0,1]
	v_pk_fma_f32 v[98:99], v[120:121], v[120:121], v[98:99]
	v_pk_add_f32 v[120:121], v[48:49], v[82:83] op_sel_hi:[1,0] neg_lo:[0,1] neg_hi:[0,1]
	v_pk_add_f32 v[122:123], v[50:51], v[82:83] op_sel_hi:[1,0] neg_lo:[0,1] neg_hi:[0,1]
	v_mov_b32_e32 v50, v121
	v_mov_b32_e32 v51, v117
	v_mov_b32_e32 v48, v120
	v_mov_b32_e32 v49, v116
	v_pk_mul_f32 v[50:51], v[50:51], v[50:51]
	v_pk_add_f32 v[118:119], v[54:55], v[82:83] op_sel_hi:[1,0] neg_lo:[0,1] neg_hi:[0,1]
	v_pk_fma_f32 v[102:103], v[48:49], v[48:49], v[50:51]
	global_load_dwordx4 v[48:51], v[104:105], off
	global_load_dwordx4 v[52:55], v[106:107], off
	v_mov_b32_e32 v104, v122
	v_mov_b32_e32 v105, v118
	v_mov_b32_e32 v106, v123
	v_mov_b32_e32 v107, v119
	v_pk_fma_f32 v[102:103], v[104:105], v[104:105], v[102:103]
	v_add_f32_e32 v82, v98, v99
	v_pk_fma_f32 v[102:103], v[106:107], v[106:107], v[102:103]
	global_load_dwordx4 v[96:99], v[96:97], off
	v_add_f32_e32 v82, v103, v82
	v_add_f32_e32 v82, v102, v82
	global_load_dwordx4 v[100:103], v[100:101], off
	s_waitcnt vmcnt(6)
	v_pk_add_f32 v[90:91], v[90:91], 1.0 op_sel_hi:[1,0]
	v_add_f32_dpp v82, v82, v82 row_ror:8 row_mask:0xf bank_mask:0xf bound_ctrl:1
	v_pk_add_f32 v[88:89], v[88:89], 1.0 op_sel_hi:[1,0]
	s_waitcnt vmcnt(2)
	v_pk_add_f32 v[54:55], v[54:55], 1.0 op_sel_hi:[1,0]
	v_add_f32_dpp v82, v82, v82 row_ror:4 row_mask:0xf bank_mask:0xf bound_ctrl:1
	v_pk_add_f32 v[52:53], v[52:53], 1.0 op_sel_hi:[1,0]
	s_nop 0
	v_add_f32_dpp v82, v82, v82 row_ror:2 row_mask:0xf bank_mask:0xf bound_ctrl:1
	s_nop 1
	v_add_f32_dpp v82, v82, v82 row_ror:1 row_mask:0xf bank_mask:0xf bound_ctrl:1
	ds_bpermute_b32 v87, v84, v82
	s_waitcnt lgkmcnt(0)
	v_add_f32_e32 v82, v82, v87
	ds_bpermute_b32 v87, v85, v82
	s_waitcnt lgkmcnt(0)
	v_add_f32_e32 v82, v82, v87
	v_fmamk_f32 v82, v82, 0x3a800000, v83
	v_mul_f32_e32 v87, 0x4b800000, v82
	v_cmp_gt_f32_e64 s[0:1], s21, v82
	s_nop 1
	v_cndmask_b32_e64 v82, v82, v87, s[0:1]
	v_rsq_f32_e32 v82, v82
	s_nop 0
	v_mul_f32_e32 v87, 0x45800000, v82
	v_cndmask_b32_e64 v82, v82, v87, s[0:1]
	v_pk_mul_f32 v[104:105], v[108:109], v[82:83] op_sel_hi:[1,0]
	v_pk_mul_f32 v[106:107], v[110:111], v[82:83] op_sel_hi:[1,0]
	v_pk_fma_f32 v[104:105], v[0:1], v[104:105], v[4:5]
	v_pk_fma_f32 v[106:107], v[2:3], v[106:107], v[6:7]
	v_pk_fma_f32 v[60:61], v[88:89], v[104:105], v[60:61]
	v_pk_fma_f32 v[62:63], v[90:91], v[106:107], v[62:63]
	v_pk_mul_f32 v[108:109], v[112:113], v[82:83] op_sel_hi:[1,0]
	v_pk_mul_f32 v[110:111], v[114:115], v[82:83] op_sel_hi:[1,0]
	v_pk_mul_f32 v[112:113], v[116:117], v[82:83] op_sel_hi:[1,0]
	v_pk_mul_f32 v[114:115], v[118:119], v[82:83] op_sel_hi:[1,0]
	v_pk_mul_f32 v[116:117], v[120:121], v[82:83] op_sel_hi:[1,0]
	v_pk_mul_f32 v[118:119], v[122:123], v[82:83] op_sel_hi:[1,0]
	v_pk_fma_f32 v[112:113], v[16:17], v[112:113], v[20:21]
	v_pk_fma_f32 v[114:115], v[18:19], v[114:115], v[22:23]
	v_cvt_pk_bf16_f32 v60, v60, v60
	v_cvt_pk_bf16_f32 v88, v61, v61
	v_cvt_pk_bf16_f32 v61, v62, v62
	v_cvt_pk_bf16_f32 v62, v63, v63
	v_pk_fma_f32 v[108:109], v[8:9], v[108:109], v[12:13]
	v_pk_fma_f32 v[110:111], v[10:11], v[110:111], v[14:15]
	v_perm_b32 v61, v62, v61, s23
	v_perm_b32 v60, v88, v60, s23
	v_pk_add_f32 v[62:63], v[94:95], 1.0 op_sel_hi:[1,0]
	v_pk_add_f32 v[88:89], v[92:93], 1.0 op_sel_hi:[1,0]
	v_pk_fma_f32 v[48:49], v[52:53], v[112:113], v[48:49]
	v_pk_fma_f32 v[50:51], v[54:55], v[114:115], v[50:51]
	v_pk_fma_f32 v[56:57], v[88:89], v[108:109], v[56:57]
	v_pk_fma_f32 v[58:59], v[62:63], v[110:111], v[58:59]
	v_cvt_pk_bf16_f32 v48, v48, v48
	v_cvt_pk_bf16_f32 v54, v49, v49
	v_cvt_pk_bf16_f32 v49, v50, v50
	v_cvt_pk_bf16_f32 v50, v51, v51
	v_cvt_pk_bf16_f32 v56, v56, v56
	v_cvt_pk_bf16_f32 v82, v57, v57
	v_cvt_pk_bf16_f32 v57, v58, v58
	v_cvt_pk_bf16_f32 v58, v59, v59
	v_perm_b32 v49, v50, v49, s23
	v_perm_b32 v48, v54, v48, s23
	v_pk_fma_f32 v[116:117], v[24:25], v[116:117], v[28:29]
	v_pk_fma_f32 v[118:119], v[26:27], v[118:119], v[30:31]
	v_perm_b32 v57, v58, v57, s23
	v_perm_b32 v56, v82, v56, s23
	global_store_dwordx4 v[124:125], v[104:107], off nt
	global_store_dwordx4 v[124:125], v[108:111], off offset:1024 nt
	global_store_dwordx4 v[124:125], v[112:115], off offset:2048 nt
	global_store_dwordx4 v[124:125], v[116:119], off offset:3072 nt
	global_store_dwordx2 v[68:69], v[60:61], off
	global_store_dwordx2 v[68:69], v[56:57], off offset:512
	global_store_dwordx2 v[68:69], v[48:49], off offset:1024
	s_waitcnt vmcnt(8)
	v_pk_add_f32 v[48:49], v[98:99], 1.0 op_sel_hi:[1,0]
	v_pk_add_f32 v[50:51], v[96:97], 1.0 op_sel_hi:[1,0]
	s_waitcnt vmcnt(7)
	v_pk_fma_f32 v[48:49], v[48:49], v[118:119], v[102:103]
	v_pk_fma_f32 v[50:51], v[50:51], v[116:117], v[100:101]
	v_cvt_pk_bf16_f32 v49, v48, v49
	v_cvt_pk_bf16_f32 v48, v50, v51
	global_store_dwordx2 v[68:69], v[48:49], off offset:1536
	v_lshl_add_u64 v[68:69], v[68:69], 0, s[8:9]
	v_mov_b32_e32 v82, v86
	v_mov_b64_e32 v[60:61], v[32:33]
	v_mov_b64_e32 v[62:63], v[34:35]
	v_mov_b64_e32 v[56:57], v[36:37]
	v_mov_b64_e32 v[58:59], v[38:39]
	v_mov_b64_e32 v[52:53], v[40:41]
	v_mov_b64_e32 v[54:55], v[42:43]
	v_mov_b64_e32 v[48:49], v[44:45]
	v_mov_b64_e32 v[50:51], v[46:47]
	s_andn2_b64 exec, exec, s[12:13]
	s_cbranch_execz .LBB0_2951

.LBB0_3119:
	s_or_b64 exec, exec, s[8:9]
	v_mov_b32_e32 v74, v57
	v_mov_b32_e32 v75, v61
	v_mov_b32_e32 v76, v56
	v_mov_b32_e32 v77, v60
	v_pk_add_f32 v[74:75], v[74:75], v[76:77]
	v_mov_b32_e32 v76, v58
	v_mov_b32_e32 v77, v62
	v_pk_add_f32 v[74:75], v[76:77], v[74:75]
	v_mov_b32_e32 v76, v59
	v_mov_b32_e32 v77, v63
	v_pk_add_f32 v[74:75], v[76:77], v[74:75]
	v_mov_b32_e32 v76, v32
	v_add_f32_e32 v75, 0, v75
	v_add_f32_e32 v78, v74, v75
	v_mov_b32_e32 v74, v33
	v_mov_b32_e32 v75, v37
	v_mov_b32_e32 v77, v36
	v_pk_add_f32 v[74:75], v[74:75], v[76:77]
	v_mov_b32_e32 v76, v34
	v_mov_b32_e32 v77, v38
	v_pk_add_f32 v[74:75], v[76:77], v[74:75]
	v_mov_b32_e32 v76, v35
	v_mov_b32_e32 v77, v39
	v_pk_add_f32 v[74:75], v[76:77], v[74:75]
	s_and_b64 s[8:9], exec, vcc
	v_add_f32_e32 v75, v75, v78
	v_add_f32_e32 v74, v74, v75
	s_or_b64 s[6:7], s[8:9], s[6:7]
	v_lshl_add_u64 v[70:71], v[70:71], 0, s[4:5]
	v_add_f32_dpp v74, v74, v74 row_ror:8 row_mask:0xf bank_mask:0xf bound_ctrl:1
	s_nop 1
	v_add_f32_dpp v74, v74, v74 row_ror:4 row_mask:0xf bank_mask:0xf bound_ctrl:1
	s_nop 1
	v_add_f32_dpp v74, v74, v74 row_ror:2 row_mask:0xf bank_mask:0xf bound_ctrl:1
	s_nop 1
	v_add_f32_dpp v74, v74, v74 row_ror:1 row_mask:0xf bank_mask:0xf bound_ctrl:1
	ds_bpermute_b32 v75, v65, v74
	s_waitcnt lgkmcnt(0)
	v_add_f32_e32 v74, v74, v75
	ds_bpermute_b32 v75, v72, v74
	s_waitcnt lgkmcnt(0)
	v_add_f32_e32 v74, v74, v75
	v_mul_f32_e32 v74, 0x3a800000, v74
	v_pk_add_f32 v[60:61], v[60:61], v[74:75] op_sel_hi:[1,0] neg_lo:[0,1] neg_hi:[0,1]
	v_pk_add_f32 v[56:57], v[56:57], v[74:75] op_sel_hi:[1,0] neg_lo:[0,1] neg_hi:[0,1]
	v_mov_b32_e32 v78, v61
	v_mov_b32_e32 v79, v57
	v_pk_add_f32 v[62:63], v[62:63], v[74:75] op_sel_hi:[1,0] neg_lo:[0,1] neg_hi:[0,1]
	v_pk_add_f32 v[58:59], v[58:59], v[74:75] op_sel_hi:[1,0] neg_lo:[0,1] neg_hi:[0,1]
	v_mov_b32_e32 v76, v60
	v_mov_b32_e32 v77, v56
	v_pk_mul_f32 v[78:79], v[78:79], v[78:79]
	v_mov_b32_e32 v80, v63
	v_pk_fma_f32 v[76:77], v[76:77], v[76:77], v[78:79]
	v_mov_b32_e32 v78, v62
	v_mov_b32_e32 v79, v58
	v_mov_b32_e32 v81, v59
	v_pk_fma_f32 v[76:77], v[78:79], v[78:79], v[76:77]
	v_pk_add_f32 v[78:79], v[36:37], v[74:75] op_sel_hi:[1,0] neg_lo:[0,1] neg_hi:[0,1]
	v_pk_add_f32 v[82:83], v[32:33], v[74:75] op_sel_hi:[1,0] neg_lo:[0,1] neg_hi:[0,1]
	v_pk_fma_f32 v[76:77], v[80:81], v[80:81], v[76:77]
	v_pk_add_f32 v[80:81], v[38:39], v[74:75] op_sel_hi:[1,0] neg_lo:[0,1] neg_hi:[0,1]
	v_pk_add_f32 v[74:75], v[34:35], v[74:75] op_sel_hi:[1,0] neg_lo:[0,1] neg_hi:[0,1]
	v_mov_b32_e32 v34, v83
	v_mov_b32_e32 v35, v79
	v_mov_b32_e32 v32, v82
	v_mov_b32_e32 v33, v78
	v_pk_mul_f32 v[34:35], v[34:35], v[34:35]
	v_mov_b32_e32 v36, v75
	v_pk_fma_f32 v[32:33], v[32:33], v[32:33], v[34:35]
	v_mov_b32_e32 v34, v74
	v_mov_b32_e32 v35, v80
	v_mov_b32_e32 v37, v81
	v_pk_fma_f32 v[32:33], v[34:35], v[34:35], v[32:33]
	v_add_f32_e32 v34, v76, v77
	v_pk_fma_f32 v[32:33], v[36:37], v[36:37], v[32:33]
	v_lshl_add_u64 v[76:77], v[68:69], 0, v[66:67]
	v_add_f32_e32 v33, v33, v34
	v_add_f32_e32 v32, v32, v33
	v_lshl_add_u64 v[68:69], v[68:69], 0, s[4:5]
	s_nop 0
	v_add_f32_dpp v32, v32, v32 row_ror:8 row_mask:0xf bank_mask:0xf bound_ctrl:1
	s_nop 1
	v_add_f32_dpp v32, v32, v32 row_ror:4 row_mask:0xf bank_mask:0xf bound_ctrl:1
	s_nop 1
	v_add_f32_dpp v32, v32, v32 row_ror:2 row_mask:0xf bank_mask:0xf bound_ctrl:1
	s_nop 1
	v_add_f32_dpp v32, v32, v32 row_ror:1 row_mask:0xf bank_mask:0xf bound_ctrl:1
	ds_bpermute_b32 v33, v65, v32
	s_waitcnt lgkmcnt(0)
	v_add_f32_e32 v32, v32, v33
	ds_bpermute_b32 v33, v72, v32
	s_waitcnt lgkmcnt(0)
	v_add_f32_e32 v32, v32, v33
	v_fmamk_f32 v32, v32, 0x3a800000, v73
	v_mul_f32_e32 v33, 0x4b800000, v32
	v_cmp_gt_f32_e64 s[0:1], s11, v32
	s_nop 1
	v_cndmask_b32_e64 v32, v32, v33, s[0:1]
	v_rsq_f32_e32 v32, v32
	s_nop 0
	v_mul_f32_e32 v33, 0x45800000, v32
	v_cndmask_b32_e64 v84, v32, v33, s[0:1]
	v_pk_mul_f32 v[32:33], v[60:61], v[84:85] op_sel_hi:[1,0]
	v_pk_mul_f32 v[34:35], v[62:63], v[84:85] op_sel_hi:[1,0]
	v_pk_mul_f32 v[36:37], v[56:57], v[84:85] op_sel_hi:[1,0]
	v_pk_mul_f32 v[38:39], v[58:59], v[84:85] op_sel_hi:[1,0]
	v_pk_mul_f32 v[56:57], v[78:79], v[84:85] op_sel_hi:[1,0]
	v_pk_mul_f32 v[58:59], v[80:81], v[84:85] op_sel_hi:[1,0]
	v_pk_mul_f32 v[60:61], v[82:83], v[84:85] op_sel_hi:[1,0]
	v_pk_mul_f32 v[62:63], v[74:75], v[84:85] op_sel_hi:[1,0]
	v_pk_fma_f32 v[32:33], v[0:1], v[32:33], v[4:5]
	v_pk_fma_f32 v[34:35], v[2:3], v[34:35], v[6:7]
	v_pk_fma_f32 v[36:37], v[8:9], v[36:37], v[12:13]
	v_pk_fma_f32 v[38:39], v[10:11], v[38:39], v[14:15]
	v_pk_fma_f32 v[56:57], v[16:17], v[56:57], v[20:21]
	v_pk_fma_f32 v[58:59], v[18:19], v[58:59], v[22:23]
	v_pk_fma_f32 v[60:61], v[24:25], v[60:61], v[28:29]
	v_pk_fma_f32 v[62:63], v[26:27], v[62:63], v[30:31]
	global_store_dwordx4 v[76:77], v[32:35], off nt
	global_store_dwordx4 v[76:77], v[36:39], off offset:1024 nt
	global_store_dwordx4 v[76:77], v[56:59], off offset:2048 nt
	global_store_dwordx4 v[76:77], v[60:63], off offset:3072 nt
	s_waitcnt vmcnt(5)
	v_mov_b64_e32 v[36:37], v[48:49]
	v_mov_b64_e32 v[56:57], v[44:45]
	v_mov_b64_e32 v[60:61], v[40:41]
	v_mov_b64_e32 v[62:63], v[42:43]
	v_mov_b64_e32 v[58:59], v[46:47]
	v_mov_b64_e32 v[38:39], v[50:51]
	s_waitcnt vmcnt(4)
	v_mov_b64_e32 v[32:33], v[52:53]
	v_mov_b64_e32 v[34:35], v[54:55]
	s_andn2_b64 exec, exec, s[6:7]
	s_cbranch_execz .LBB0_3122
